# attention: K tiles staged two ahead; the next tile's first K fragment pair is read before the step-closing barrier (no LDS latency at the step head); on top of v58
# baseline (speedup 1.0000x reference)
; #define WAIT_BAR() asm volatile("s_waitcnt vmcnt(0) lgkmcnt(0)\n\ts_barrier" ::: "memory")
;     ...
;     f32x16 pA0, pA1, pB0, pB1; float alA, alB; bf16x8 pa0, pa1, pa2, pa3;
;     int sp = 0, sc_ = 1, sn = 2;
;     ...
;     if (wid >= 4) __builtin_amdgcn_s_setprio(1);
;     DMA(0, 0); DMA(1, 1); WAIT_BAR();
;     { qkt(pA0, pA1, K_lds, qr, r32, hi); rowdecide(rowmax16(pA0), pA0, pA1, negm, alA);
; #pragma unroll
;       for (int r = 0; r < 16; ++r) { pA0[r] = __builtin_amdgcn_exp2f(pA0[r]); pA1[r] = __builtin_amdgcn_exp2f(pA1[r]); } }
;     for (int j = 1; j + 1 < NT; j += 2) {
;       STEP(pB0, pB1, pA0, pA1, alA, alB, DMA(j + 1, sn));
.LBB0_694:
	s_lshl_b32 s0, s23, 1
	s_and_b32 s43, s0, 0x700
	s_and_b32 s0, s4, 0x3fffffc0
	s_lshl_b32 s0, s0, 2
	s_add_i32 s19, s0, 0
	s_add_i32 s19, s19, 0x12000
	s_cmp_lg_u32 0, -1
	s_cselect_b32 s0, 0, 0
	v_lshlrev_b32_e32 v36, 4, v169
	s_add_i32 s39, s0, s24
	v_lshlrev_b32_e32 v35, 3, v169
	v_and_b32_e32 v36, 0xc0, v36
	v_lshlrev_b32_e32 v37, 1, v169
	v_exp_f32_e32 v96, v16
	v_exp_f32_e32 v80, v0
	v_exp_f32_e32 v97, v17
	v_exp_f32_e32 v81, v1
	v_exp_f32_e32 v98, v18
	v_exp_f32_e32 v82, v2
	v_exp_f32_e32 v99, v19
	v_exp_f32_e32 v83, v3
	v_exp_f32_e32 v100, v20
	v_exp_f32_e32 v84, v4
	v_exp_f32_e32 v101, v21
	v_exp_f32_e32 v85, v5
	v_exp_f32_e32 v102, v22
	v_exp_f32_e32 v86, v6
	v_exp_f32_e32 v103, v23
	v_exp_f32_e32 v87, v7
	v_exp_f32_e32 v104, v24
	v_exp_f32_e32 v88, v8
	v_exp_f32_e32 v105, v25
	v_exp_f32_e32 v89, v9
	v_exp_f32_e32 v106, v26
	v_exp_f32_e32 v90, v10
	v_exp_f32_e32 v107, v27
	v_exp_f32_e32 v91, v11
	v_exp_f32_e32 v108, v28
	v_exp_f32_e32 v92, v12
	v_exp_f32_e32 v109, v29
	v_exp_f32_e32 v93, v13
	v_exp_f32_e32 v110, v30
	v_exp_f32_e32 v94, v14
	v_exp_f32_e32 v111, v31
	v_exp_f32_e32 v95, v15
	s_add_i32 s39, s39, 0xc000
	s_or_b32 s4, s42, s43
	v_and_or_b32 v36, v35, 24, v36
	v_and_b32_e32 v37, 32, v37
	v_and_b32_e32 v35, 0x100, v35
	s_add_u32 s4, s16, s4
	v_mov_b32_e32 v48, v167
	v_mov_b32_e32 v49, v167
	v_or3_b32 v179, v36, v37, v35
	v_lshl_add_u32 v177, v34, 2, s19
	s_addc_u32 s5, s17, s5
	v_lshl_add_u64 v[172:173], v[32:33], 0, s[10:11]
	v_mov_b32_e32 v50, v167
	v_mov_b32_e32 v51, v167
	v_mov_b32_e32 v52, v167
	v_mov_b32_e32 v53, v167
	v_mov_b32_e32 v54, v167
	v_mov_b32_e32 v55, v167
	v_mov_b32_e32 v56, v167
	v_mov_b32_e32 v57, v167
	v_mov_b32_e32 v58, v167
	v_mov_b32_e32 v59, v167
	v_mov_b32_e32 v60, v167
	v_mov_b32_e32 v61, v167
	v_mov_b32_e32 v62, v167
	v_mov_b32_e32 v63, v167
	v_mov_b64_e32 v[32:33], v[48:49]
	v_mov_b64_e32 v[16:17], v[48:49]
	v_mov_b64_e32 v[0:1], v[48:49]
	s_mov_b32 s38, 1
	s_mov_b32 s34, 2
	s_mov_b32 s35, -1
	s_mov_b32 s44, 0
	v_add_u32_e32 v183, s0, v179
	v_cmp_gt_u32_e64 s[0:1], 32, v169
	v_add3_u32 v184, 0, v181, v180
	v_mov_b32_e32 v178, 0
	s_mov_b64 s[68:69], s[4:5]
	v_mov_b64_e32 v[34:35], v[50:51]
	v_mov_b64_e32 v[36:37], v[52:53]
	v_mov_b64_e32 v[38:39], v[54:55]
	v_mov_b64_e32 v[40:41], v[56:57]
	v_mov_b64_e32 v[42:43], v[58:59]
	v_mov_b64_e32 v[44:45], v[60:61]
	v_mov_b64_e32 v[46:47], v[62:63]
	v_mov_b64_e32 v[18:19], v[50:51]
	v_mov_b64_e32 v[20:21], v[52:53]
	v_mov_b64_e32 v[22:23], v[54:55]
	v_mov_b64_e32 v[24:25], v[56:57]
	v_mov_b64_e32 v[26:27], v[58:59]
	v_mov_b64_e32 v[28:29], v[60:61]
	v_mov_b64_e32 v[30:31], v[62:63]
	v_mov_b64_e32 v[2:3], v[50:51]
	v_mov_b64_e32 v[4:5], v[52:53]
	v_mov_b64_e32 v[6:7], v[54:55]
	v_mov_b64_e32 v[8:9], v[56:57]
	v_mov_b64_e32 v[10:11], v[58:59]
	v_mov_b64_e32 v[12:13], v[60:61]
	v_mov_b64_e32 v[14:15], v[62:63]
	s_lshl_b32 s48, s34, 13
	s_add_i32 s48, s48, s39
	s_mov_b32 m0, s48
	s_nop 0
	global_load_lds_dwordx4 v[172:173], off
	v_lshl_add_u64 v[172:173], v[172:173], 0, s[8:9]
	s_waitcnt vmcnt(0)
	s_barrier
	v_lshl_add_u32 v236, s38, 13, v184
	ds_read_b128 v[228:231], v236 offset:49152
	ds_read_b128 v[232:235], v236 offset:49664
.LBB0_695:
	s_lshl_b32 s43, s34, 13
	s_mov_b32 s42, s38
	v_lshl_add_u32 v185, s42, 13, v184
	s_mov_b32 s38, s44
	s_cmp_lt_i32 s18, 4
	s_cbranch_scc1 .Lattn_nodma_Lattn_m0_res1
	s_lshl_b32 s98, s38, 13
	s_add_i32 s98, s98, s39
	s_mov_b32 m0, s98
	s_mov_b32 s100, 0xffffffc0
	s_mov_b32 s101, -1
	global_load_lds_dwordx4 v[172:173], off
	s_addk_i32 s98, 0xf000
	s_mov_b32 m0, s98
	v_lshl_add_u64 v[212:213], v[172:173], 0, s[100:101]
	global_load_lds_dwordx4 v[212:213], off
	s_lshl_b32 s98, s34, 14
	s_add_i32 s99, s98, s24
	s_mov_b32 m0, s99
	v_lshl_add_u64 v[212:213], s[68:69], 0, v[166:167]
	global_load_lds_dwordx4 v[212:213], off
	s_add_u32 s100, s68, 0xffff8000
	s_addc_u32 s101, s69, -1
	s_addk_i32 s99, 0xf000
	s_mov_b32 m0, s99
	v_lshl_add_u64 v[214:215], s[100:101], 0, v[166:167]
	global_load_lds_dwordx4 v[214:215], off
	s_add_i32 s98, s98, s25
	s_mov_b32 m0, s98
	v_lshl_add_u64 v[212:213], s[68:69], 0, v[170:171]
	global_load_lds_dwordx4 v[212:213], off
	s_addk_i32 s98, 0xf000
	s_mov_b32 m0, s98
	v_lshl_add_u64 v[214:215], s[100:101], 0, v[170:171]
	global_load_lds_dwordx4 v[214:215], off
.Lattn_nodma_Lattn_m0_res1:
	s_waitcnt lgkmcnt(1)
	v_mfma_f32_32x32x16_bf16 v[128:143], v[228:231], v[156:159], v[64:79]
	ds_read_b128 v[190:193], v185 offset:51200
	ds_read_b128 v[194:197], v185 offset:51712
	v_add_f32_e32 v116, v98, v96
	v_add_f32_e32 v117, v99, v97
	v_cvt_pk_bf16_f32 v96, v96, v97
	v_cvt_pk_bf16_f32 v97, v98, v99
	v_cvt_pk_bf16_f32 v98, v100, v101
	v_cvt_pk_bf16_f32 v99, v102, v103
	v_add_f32_e32 v100, v100, v116
	v_add_f32_e32 v101, v101, v117
	s_waitcnt lgkmcnt(2)
	v_mfma_f32_32x32x16_bf16 v[112:127], v[232:235], v[156:159], v[64:79]
	v_add_f32_e32 v100, v102, v100
	v_add_f32_e32 v101, v103, v101
	s_waitcnt lgkmcnt(1)
	v_mfma_f32_32x32x16_bf16 v[128:143], v[190:193], v[152:155], v[128:143]
	ds_read_b128 v[186:189], v185 offset:53248
	ds_read_b128 v[198:201], v185 offset:53760
	v_add_f32_e32 v100, v104, v100
	v_add_f32_e32 v101, v105, v101
	v_add_f32_e32 v202, v106, v100
	v_add_f32_e32 v203, v107, v101
	v_cvt_pk_bf16_f32 v100, v104, v105
	v_cvt_pk_bf16_f32 v101, v106, v107
	v_cvt_pk_bf16_f32 v102, v108, v109
	v_cvt_pk_bf16_f32 v103, v110, v111
	s_waitcnt lgkmcnt(2)
	v_mfma_f32_32x32x16_bf16 v[112:127], v[194:197], v[152:155], v[112:127]
	v_add_f32_e32 v104, v108, v202
	v_add_f32_e32 v105, v109, v203
	v_add_f32_e32 v190, v110, v104
	v_add_f32_e32 v191, v111, v105
	s_waitcnt lgkmcnt(1)
	v_mfma_f32_32x32x16_bf16 v[128:143], v[186:189], v[148:151], v[128:143]
	ds_read_b128 v[104:107], v185 offset:55296
	ds_read_b128 v[108:111], v185 offset:55808
	v_add_f32_e32 v185, v80, v190
	v_add_f32_e32 v190, v81, v191
	v_add_f32_e32 v185, v82, v185
	v_add_f32_e32 v190, v83, v190
	v_cvt_pk_bf16_f32 v80, v80, v81
	v_cvt_pk_bf16_f32 v81, v82, v83
	v_cvt_pk_bf16_f32 v82, v84, v85
	v_cvt_pk_bf16_f32 v83, v86, v87
	s_waitcnt lgkmcnt(2)
	v_mfma_f32_32x32x16_bf16 v[112:127], v[198:201], v[148:151], v[112:127]
	s_lshl_b32 s44, s38, 14
	v_add_u32_e32 v189, s44, v183
	ds_read_b64_tr_b16 v[194:195], v189 offset:0
	ds_read_b64_tr_b16 v[196:197], v189 offset:0x800
	ds_read_b64_tr_b16 v[212:213], v189 offset:0x1000
	ds_read_b64_tr_b16 v[214:215], v189 offset:0x1800
	ds_read_b64_tr_b16 v[216:217], v189 offset:0x2000
	ds_read_b64_tr_b16 v[218:219], v189 offset:0x2800
	v_add_f32_e32 v84, v84, v185
	v_add_f32_e32 v85, v85, v190
	v_add_f32_e32 v84, v86, v84
	v_add_f32_e32 v85, v87, v85
	s_waitcnt lgkmcnt(7)
	v_mfma_f32_32x32x16_bf16 v[128:143], v[104:107], v[144:147], v[128:143]
	ds_read_b64_tr_b16 v[198:199], v189 offset:0x3000
	ds_read_b64_tr_b16 v[200:201], v189 offset:0x3800
	ds_read_b64_tr_b16 v[190:191], v189 offset:0x200
	ds_read_b64_tr_b16 v[192:193], v189 offset:0xa00
	v_add_f32_e32 v84, v88, v84
	v_add_f32_e32 v85, v89, v85
	v_add_f32_e32 v185, v90, v84
	v_add_f32_e32 v186, v91, v85
	v_cvt_pk_bf16_f32 v84, v88, v89
	v_cvt_pk_bf16_f32 v85, v90, v91
	v_cvt_pk_bf16_f32 v86, v92, v93
	v_cvt_pk_bf16_f32 v87, v94, v95
	s_waitcnt lgkmcnt(10)
	v_mfma_f32_32x32x16_bf16 v[112:127], v[108:111], v[144:147], v[112:127]
	v_add_f32_e32 v88, v92, v185
	v_add_f32_e32 v89, v93, v186
	v_add_f32_e32 v88, v94, v88
	v_add_f32_e32 v89, v95, v89
	ds_read_b64_tr_b16 v[220:221], v189 offset:0x1200
	ds_read_b64_tr_b16 v[222:223], v189 offset:0x1a00
	ds_read_b64_tr_b16 v[224:225], v189 offset:0x2200
	ds_read_b64_tr_b16 v[226:227], v189 offset:0x2a00
	s_waitcnt lgkmcnt(12)
	v_mfma_f32_32x32x16_bf16 v[48:63], v[96:99], v[194:197], v[48:63]
	v_max_f32_e32 v90, v128, v129
	v_max3_f32 v91, v131, v132, v133
	v_max3_f32 v90, v90, v130, v134
	v_max3_f32 v91, v91, v136, v137
	ds_read_b64_tr_b16 v[194:195], v189 offset:0x3200
	ds_read_b64_tr_b16 v[196:197], v189 offset:0x3a00
	s_waitcnt lgkmcnt(12)
	v_mfma_f32_32x32x16_bf16 v[48:63], v[100:103], v[212:215], v[48:63]
	v_max3_f32 v90, v90, v135, v138
	v_max3_f32 v91, v91, v140, v141
	v_max3_f32 v90, v90, v139, v142
	v_max3_f32 v90, v90, v143, v91
	v_add_f32_e32 v186, v88, v89
	v_mov_b32_e32 v187, v186
	ds_read_b64_tr_b16 v[212:213], v189 offset:0x400
	ds_read_b64_tr_b16 v[214:215], v189 offset:0xc00
	s_waitcnt lgkmcnt(12)
	v_mfma_f32_32x32x16_bf16 v[48:63], v[80:83], v[216:219], v[48:63]
	v_max3_f32 v88, v112, v113, v114
	v_max3_f32 v89, v115, v116, v117
	v_max3_f32 v88, v88, v118, v119
	v_max3_f32 v89, v89, v120, v121
	v_permlane32_swap_b32_e32 v186, v187
	v_max3_f32 v88, v88, v122, v123
	ds_read_b64_tr_b16 v[216:217], v189 offset:0x1400
	ds_read_b64_tr_b16 v[218:219], v189 offset:0x1c00
	s_waitcnt lgkmcnt(12)
	v_mfma_f32_32x32x16_bf16 v[48:63], v[84:87], v[198:201], v[48:63]
	v_max3_f32 v89, v89, v124, v125
	v_max3_f32 v88, v88, v126, v127
	v_max3_f32 v88, v90, v88, v89
	v_mov_b32_e32 v89, v88
	ds_read_b64_tr_b16 v[198:199], v189 offset:0x2400
	ds_read_b64_tr_b16 v[200:201], v189 offset:0x2c00
	s_waitcnt lgkmcnt(12)
	v_mfma_f32_32x32x16_bf16 v[32:47], v[96:99], v[190:193], v[32:47]
	v_permlane32_swap_b32_e32 v88, v89
	v_max_f32_e32 v88, v88, v89
	v_cmp_lt_f32_e32 vcc, s47, v88
	v_mov_b32_e32 v188, 1.0
	s_cbranch_vccnz .LBB0_707
; #define WAIT_BAR() asm volatile("s_waitcnt vmcnt(0) lgkmcnt(0)\n\ts_barrier" ::: "memory")
; #define RESC(a) do { if (__any((a) < 1.f)) { if (hi == 0) al_l[r32] = (a); asm volatile("s_waitcnt lgkmcnt(0)" ::: "memory"); \
;     _Pragma("unroll") for (int d = 0; d < 4; ++d) _Pragma("unroll") for (int r = 0; r < 16; ++r) o[d][r] *= al_l[crow(r, hi)]; } } while (0)
; #define ROT() do { const int t_ = sp; sp = sc_; sc_ = sn; sn = t_; } while (0)
;     ...
;     if (wid >= 4) __builtin_amdgcn_s_setprio(1);
;     DMA(0, 0); DMA(1, 1); WAIT_BAR();
;     { qkt(pA0, pA1, K_lds, qr, r32, hi); rowdecide(rowmax16(pA0), pA0, pA1, negm, alA);
; #pragma unroll
;       for (int r = 0; r < 16; ++r) { pA0[r] = __builtin_amdgcn_exp2f(pA0[r]); pA1[r] = __builtin_amdgcn_exp2f(pA1[r]); } }
;     for (int j = 1; j + 1 < NT; j += 2) {
;       STEP(pB0, pB1, pA0, pA1, alA, alB, DMA(j + 1, sn));
;       RESC(alB); WAIT_BAR(); ROT();
;       STEP(pA0, pA1, pB0, pB1, alB, alA, DMA(j + 2, sn));
.Lattn_m0_res1:
	ds_read_b64_tr_b16 v[190:191], v189 offset:0x3400
	ds_read_b64_tr_b16 v[192:193], v189 offset:0x3c00
	s_waitcnt lgkmcnt(12)
	v_mfma_f32_32x32x16_bf16 v[32:47], v[100:103], v[220:223], v[32:47]
	v_exp_f32_e32 v128, v128
	v_exp_f32_e32 v129, v129
	v_exp_f32_e32 v130, v130
	ds_read_b64_tr_b16 v[220:221], v189 offset:0x600
	ds_read_b64_tr_b16 v[222:223], v189 offset:0xe00
	s_waitcnt lgkmcnt(12)
	v_mfma_f32_32x32x16_bf16 v[32:47], v[80:83], v[224:227], v[32:47]
	v_exp_f32_e32 v131, v131
	v_exp_f32_e32 v132, v132
	v_exp_f32_e32 v133, v133
	ds_read_b64_tr_b16 v[224:225], v189 offset:0x1600
	ds_read_b64_tr_b16 v[226:227], v189 offset:0x1e00
	s_waitcnt lgkmcnt(12)
	v_mfma_f32_32x32x16_bf16 v[32:47], v[84:87], v[194:197], v[32:47]
	v_exp_f32_e32 v134, v134
	v_exp_f32_e32 v135, v135
	v_exp_f32_e32 v136, v136
	ds_read_b64_tr_b16 v[194:195], v189 offset:0x2600
	ds_read_b64_tr_b16 v[196:197], v189 offset:0x2e00
	s_waitcnt lgkmcnt(12)
	v_mfma_f32_32x32x16_bf16 v[16:31], v[96:99], v[212:215], v[16:31]
	v_exp_f32_e32 v137, v137
	v_exp_f32_e32 v138, v138
	v_exp_f32_e32 v139, v139
	ds_read_b64_tr_b16 v[212:213], v189 offset:0x3600
	ds_read_b64_tr_b16 v[214:215], v189 offset:0x3e00
	s_waitcnt lgkmcnt(12)
	v_mfma_f32_32x32x16_bf16 v[16:31], v[100:103], v[216:219], v[16:31]
	v_exp_f32_e32 v140, v140
	v_exp_f32_e32 v141, v141
	v_exp_f32_e32 v142, v142
	s_waitcnt lgkmcnt(10)
	v_mfma_f32_32x32x16_bf16 v[16:31], v[80:83], v[198:201], v[16:31]
	v_exp_f32_e32 v143, v143
	v_exp_f32_e32 v112, v112
	v_exp_f32_e32 v113, v113
	s_waitcnt lgkmcnt(8)
	v_mfma_f32_32x32x16_bf16 v[16:31], v[84:87], v[190:193], v[16:31]
	v_exp_f32_e32 v114, v114
	v_exp_f32_e32 v115, v115
	v_exp_f32_e32 v116, v116
	s_waitcnt lgkmcnt(6)
	v_mfma_f32_32x32x16_bf16 v[0:15], v[96:99], v[220:223], v[0:15]
	v_exp_f32_e32 v117, v117
	v_exp_f32_e32 v118, v118
	v_exp_f32_e32 v119, v119
	v_lshl_add_u32 v236, s34, 13, v184
	ds_read_b128 v[228:231], v236 offset:49152
	ds_read_b128 v[232:235], v236 offset:49664
	s_waitcnt lgkmcnt(6)
	v_mfma_f32_32x32x16_bf16 v[0:15], v[100:103], v[224:227], v[0:15]
	v_exp_f32_e32 v120, v120
	v_exp_f32_e32 v121, v121
	v_exp_f32_e32 v122, v122
	s_waitcnt lgkmcnt(4)
	v_mfma_f32_32x32x16_bf16 v[0:15], v[80:83], v[194:197], v[0:15]
	v_exp_f32_e32 v123, v123
	v_exp_f32_e32 v124, v124
	v_exp_f32_e32 v125, v125
	s_waitcnt lgkmcnt(2)
	v_mfma_f32_32x32x16_bf16 v[0:15], v[84:87], v[212:215], v[0:15]
	v_exp_f32_e32 v126, v126
	v_exp_f32_e32 v127, v127
	v_cmp_gt_f32_e32 vcc, 1.0, v188
	s_cbranch_vccz .LBB0_700
	s_and_saveexec_b64 s[70:71], s[0:1]
	ds_write_b32 v177, v188 offset:128
	s_or_b64 exec, exec, s[70:71]
	s_waitcnt lgkmcnt(0)
	v_add_u32_e32 v92, s19, v168
	ds_read_b128 v[80:83], v92 offset:224
	ds_read_b128 v[84:87], v92 offset:192
	ds_read_b128 v[88:91], v92 offset:160
	ds_read_b128 v[92:95], v92 offset:128
	s_waitcnt lgkmcnt(3)
	v_pk_mul_f32 v[60:61], v[60:61], v[80:81]
	s_waitcnt lgkmcnt(2)
	v_pk_mul_f32 v[56:57], v[56:57], v[84:85]
	s_waitcnt lgkmcnt(1)
	v_pk_mul_f32 v[52:53], v[52:53], v[88:89]
	v_pk_mul_f32 v[62:63], v[62:63], v[82:83]
	v_pk_mul_f32 v[58:59], v[58:59], v[86:87]
	v_pk_mul_f32 v[54:55], v[54:55], v[90:91]
	s_waitcnt lgkmcnt(0)
	v_pk_mul_f32 v[50:51], v[50:51], v[94:95]
	v_pk_mul_f32 v[48:49], v[48:49], v[92:93]
	v_pk_mul_f32 v[44:45], v[44:45], v[80:81]
	v_pk_mul_f32 v[40:41], v[40:41], v[84:85]
	v_pk_mul_f32 v[36:37], v[36:37], v[88:89]
	v_pk_mul_f32 v[46:47], v[46:47], v[82:83]
	v_pk_mul_f32 v[42:43], v[42:43], v[86:87]
	v_pk_mul_f32 v[38:39], v[38:39], v[90:91]
	v_pk_mul_f32 v[34:35], v[34:35], v[94:95]
	v_pk_mul_f32 v[32:33], v[32:33], v[92:93]
	v_pk_mul_f32 v[28:29], v[28:29], v[80:81]
	v_pk_mul_f32 v[24:25], v[24:25], v[84:85]
	v_pk_mul_f32 v[20:21], v[20:21], v[88:89]
	v_pk_mul_f32 v[30:31], v[30:31], v[82:83]
	v_pk_mul_f32 v[26:27], v[26:27], v[86:87]
	v_pk_mul_f32 v[22:23], v[22:23], v[90:91]
	v_pk_mul_f32 v[18:19], v[18:19], v[94:95]
	v_pk_mul_f32 v[16:17], v[16:17], v[92:93]
	v_pk_mul_f32 v[12:13], v[12:13], v[80:81]
	v_pk_mul_f32 v[8:9], v[8:9], v[84:85]
	v_pk_mul_f32 v[4:5], v[4:5], v[88:89]
	v_pk_mul_f32 v[14:15], v[14:15], v[82:83]
	v_pk_mul_f32 v[10:11], v[10:11], v[86:87]
	v_pk_mul_f32 v[6:7], v[6:7], v[90:91]
	v_pk_mul_f32 v[2:3], v[2:3], v[94:95]
	v_pk_mul_f32 v[0:1], v[0:1], v[92:93]
.LBB0_700:
	s_add_u32 s48, s68, 0x20000
	s_addc_u32 s49, s69, 0
	s_lshl_b32 s45, s42, 13
	s_add_i32 s45, s45, s39
	s_waitcnt vmcnt(0)
	s_barrier
	v_add_u32_e32 v185, s43, v184
	s_cmp_lt_i32 s18, 4
	s_cbranch_scc1 .Lattn_nodma_Lattn_m0_res2
	s_cmp_eq_u32 s35, 0x7f
	s_cbranch_scc1 .Lattn_skipk_Lattn_m0_res2
	s_mov_b32 m0, s45
	v_lshl_add_u64 v[212:213], v[172:173], 0, s[8:9]
	global_load_lds_dwordx4 v[212:213], off
	s_add_i32 s98, s45, 0xfffff000
	s_mov_b32 m0, s98
	s_mov_b32 s100, 0xffffffc0
	s_mov_b32 s101, -1
	v_lshl_add_u64 v[214:215], v[212:213], 0, s[100:101]
	global_load_lds_dwordx4 v[214:215], off
.Lattn_skipk_Lattn_m0_res2:
	s_add_i32 s99, s44, s24
	s_mov_b32 m0, s99
	v_lshl_add_u64 v[212:213], s[48:49], 0, v[166:167]
	global_load_lds_dwordx4 v[212:213], off
	s_add_u32 s100, s48, 0xffff8000
	s_addc_u32 s101, s49, -1
	s_addk_i32 s99, 0xf000
	s_mov_b32 m0, s99
	v_lshl_add_u64 v[214:215], s[100:101], 0, v[166:167]
	global_load_lds_dwordx4 v[214:215], off
	s_add_i32 s98, s44, s25
	s_mov_b32 m0, s98
	v_lshl_add_u64 v[212:213], s[48:49], 0, v[170:171]
	global_load_lds_dwordx4 v[212:213], off
	s_addk_i32 s98, 0xf000
	s_mov_b32 m0, s98
	v_lshl_add_u64 v[214:215], s[100:101], 0, v[170:171]
	global_load_lds_dwordx4 v[214:215], off
.Lattn_nodma_Lattn_m0_res2:
	s_add_i32 s44, s44, s25
	s_waitcnt lgkmcnt(1)
	v_mfma_f32_32x32x16_bf16 v[96:111], v[228:231], v[156:159], v[64:79]
	ds_read_b128 v[194:197], v185 offset:51200
	ds_read_b128 v[198:201], v185 offset:51712
	v_add_f32_e32 v84, v130, v128
	v_add_f32_e32 v85, v131, v129
	v_cvt_pk_bf16_f32 v128, v128, v129
	v_cvt_pk_bf16_f32 v129, v130, v131
	v_cvt_pk_bf16_f32 v130, v132, v133
	v_cvt_pk_bf16_f32 v131, v134, v135
	v_add_f32_e32 v80, v132, v84
	v_add_f32_e32 v81, v133, v85
	v_add_f32_e32 v132, v134, v80
	v_add_f32_e32 v133, v135, v81
	s_waitcnt lgkmcnt(2)
	v_mfma_f32_32x32x16_bf16 v[80:95], v[232:235], v[156:159], v[64:79]
	s_waitcnt lgkmcnt(1)
	v_mfma_f32_32x32x16_bf16 v[96:111], v[194:197], v[152:155], v[96:111]
	ds_read_b128 v[190:193], v185 offset:53248
	ds_read_b128 v[202:205], v185 offset:53760
	v_add_f32_e32 v132, v136, v132
	v_add_f32_e32 v133, v137, v133
	v_add_f32_e32 v189, v138, v132
	v_add_f32_e32 v206, v139, v133
	v_cvt_pk_bf16_f32 v132, v136, v137
	v_cvt_pk_bf16_f32 v133, v138, v139
	v_cvt_pk_bf16_f32 v134, v140, v141
	v_cvt_pk_bf16_f32 v135, v142, v143
	s_waitcnt lgkmcnt(2)
	v_mfma_f32_32x32x16_bf16 v[80:95], v[198:201], v[152:155], v[80:95]
	v_add_f32_e32 v136, v140, v189
	v_add_f32_e32 v137, v141, v206
	v_add_f32_e32 v189, v142, v136
	v_add_f32_e32 v194, v143, v137
	s_waitcnt lgkmcnt(1)
	v_mfma_f32_32x32x16_bf16 v[96:111], v[190:193], v[148:151], v[96:111]
	ds_read_b128 v[136:139], v185 offset:55296
	ds_read_b128 v[140:143], v185 offset:55808
	v_add_f32_e32 v185, v112, v189
	v_add_f32_e32 v189, v113, v194
	v_add_f32_e32 v185, v114, v185
	v_add_f32_e32 v189, v115, v189
	v_cvt_pk_bf16_f32 v112, v112, v113
	v_cvt_pk_bf16_f32 v113, v114, v115
	v_cvt_pk_bf16_f32 v114, v116, v117
	v_cvt_pk_bf16_f32 v115, v118, v119
	s_waitcnt lgkmcnt(2)
	v_mfma_f32_32x32x16_bf16 v[80:95], v[202:205], v[148:151], v[80:95]
	v_lshl_add_u32 v206, s42, 14, v183
	ds_read_b64_tr_b16 v[198:199], v206 offset:0
	ds_read_b64_tr_b16 v[200:201], v206 offset:0x800
	ds_read_b64_tr_b16 v[190:191], v206 offset:0x1000
	ds_read_b64_tr_b16 v[192:193], v206 offset:0x1800
	ds_read_b64_tr_b16 v[212:213], v206 offset:0x2000
	ds_read_b64_tr_b16 v[214:215], v206 offset:0x2800
	v_add_f32_e32 v116, v116, v185
	v_add_f32_e32 v117, v117, v189
	v_add_f32_e32 v116, v118, v116
	v_add_f32_e32 v117, v119, v117
	s_waitcnt lgkmcnt(7)
	v_mfma_f32_32x32x16_bf16 v[96:111], v[136:139], v[144:147], v[96:111]
	ds_read_b64_tr_b16 v[202:203], v206 offset:0x3000
	ds_read_b64_tr_b16 v[204:205], v206 offset:0x3800
	ds_read_b64_tr_b16 v[216:217], v206 offset:0x200
	ds_read_b64_tr_b16 v[218:219], v206 offset:0xa00
	v_add_f32_e32 v116, v120, v116
	v_add_f32_e32 v117, v121, v117
	v_add_f32_e32 v185, v122, v116
	v_add_f32_e32 v189, v123, v117
	v_cvt_pk_bf16_f32 v116, v120, v121
	v_cvt_pk_bf16_f32 v117, v122, v123
	v_cvt_pk_bf16_f32 v118, v124, v125
	v_cvt_pk_bf16_f32 v119, v126, v127
	s_waitcnt lgkmcnt(10)
	v_mfma_f32_32x32x16_bf16 v[80:95], v[140:143], v[144:147], v[80:95]
	v_add_f32_e32 v120, v124, v185
	v_add_f32_e32 v121, v125, v189
	v_add_f32_e32 v120, v126, v120
	v_add_f32_e32 v121, v127, v121
	ds_read_b64_tr_b16 v[220:221], v206 offset:0x1200
	ds_read_b64_tr_b16 v[222:223], v206 offset:0x1a00
	ds_read_b64_tr_b16 v[224:225], v206 offset:0x2200
	ds_read_b64_tr_b16 v[226:227], v206 offset:0x2a00
	s_waitcnt lgkmcnt(12)
	v_mfma_f32_32x32x16_bf16 v[48:63], v[128:131], v[198:201], v[48:63]
	v_max_f32_e32 v122, v96, v97
	v_max3_f32 v123, v99, v100, v101
	v_max3_f32 v122, v122, v98, v102
	v_max3_f32 v123, v123, v104, v105
	ds_read_b64_tr_b16 v[198:199], v206 offset:0x3200
	ds_read_b64_tr_b16 v[200:201], v206 offset:0x3a00
	s_waitcnt lgkmcnt(12)
	v_mfma_f32_32x32x16_bf16 v[48:63], v[132:135], v[190:193], v[48:63]
	v_max3_f32 v122, v122, v103, v106
	v_max3_f32 v123, v123, v108, v109
	v_max3_f32 v122, v122, v107, v110
	v_max3_f32 v122, v122, v111, v123
	v_add_f32_e32 v120, v120, v121
	v_mov_b32_e32 v121, v120
	ds_read_b64_tr_b16 v[190:191], v206 offset:0x400
	ds_read_b64_tr_b16 v[192:193], v206 offset:0xc00
	s_waitcnt lgkmcnt(12)
	v_mfma_f32_32x32x16_bf16 v[48:63], v[112:115], v[212:215], v[48:63]
	v_max3_f32 v123, v80, v81, v82
	v_max3_f32 v124, v83, v84, v85
	v_max3_f32 v123, v123, v86, v87
	v_max3_f32 v124, v124, v88, v89
	v_permlane32_swap_b32_e32 v120, v121
	v_max3_f32 v123, v123, v90, v91
	ds_read_b64_tr_b16 v[212:213], v206 offset:0x1400
	ds_read_b64_tr_b16 v[214:215], v206 offset:0x1c00
	s_waitcnt lgkmcnt(12)
	v_mfma_f32_32x32x16_bf16 v[48:63], v[116:119], v[202:205], v[48:63]
	v_max3_f32 v124, v124, v92, v93
	v_max3_f32 v123, v123, v94, v95
	v_max3_f32 v122, v122, v123, v124
	v_mov_b32_e32 v123, v122
	ds_read_b64_tr_b16 v[202:203], v206 offset:0x2400
	ds_read_b64_tr_b16 v[204:205], v206 offset:0x2c00
	s_waitcnt lgkmcnt(12)
	v_mfma_f32_32x32x16_bf16 v[32:47], v[128:131], v[216:219], v[32:47]
	v_permlane32_swap_b32_e32 v122, v123
	v_max_f32_e32 v122, v122, v123
	v_cmp_lt_f32_e32 vcc, s47, v122
	v_mov_b32_e32 v185, 1.0
	s_cbranch_vccnz .LBB0_708
; #define WAIT_BAR() asm volatile("s_waitcnt vmcnt(0) lgkmcnt(0)\n\ts_barrier" ::: "memory")
; #define RESC(a) do { if (__any((a) < 1.f)) { if (hi == 0) al_l[r32] = (a); asm volatile("s_waitcnt lgkmcnt(0)" ::: "memory"); \
;     _Pragma("unroll") for (int d = 0; d < 4; ++d) _Pragma("unroll") for (int r = 0; r < 16; ++r) o[d][r] *= al_l[crow(r, hi)]; } } while (0)
; #define ROT() do { const int t_ = sp; sp = sc_; sc_ = sn; sn = t_; } while (0)
;     ...
;     if (wid >= 4) __builtin_amdgcn_s_setprio(1);
;     DMA(0, 0); DMA(1, 1); WAIT_BAR();
;     { qkt(pA0, pA1, K_lds, qr, r32, hi); rowdecide(rowmax16(pA0), pA0, pA1, negm, alA);
; #pragma unroll
;       for (int r = 0; r < 16; ++r) { pA0[r] = __builtin_amdgcn_exp2f(pA0[r]); pA1[r] = __builtin_amdgcn_exp2f(pA1[r]); } }
;     for (int j = 1; j + 1 < NT; j += 2) {
;       STEP(pB0, pB1, pA0, pA1, alA, alB, DMA(j + 1, sn));
;       RESC(alB); WAIT_BAR(); ROT();
;       STEP(pA0, pA1, pB0, pB1, alB, alA, DMA(j + 2, sn));
;       RESC(alA); WAIT_BAR(); ROT();
.Lattn_m0_res2:
	ds_read_b64_tr_b16 v[216:217], v206 offset:0x3400
	ds_read_b64_tr_b16 v[218:219], v206 offset:0x3c00
	s_waitcnt lgkmcnt(12)
	v_mfma_f32_32x32x16_bf16 v[32:47], v[132:135], v[220:223], v[32:47]
	v_exp_f32_e32 v96, v96
	v_exp_f32_e32 v97, v97
	v_exp_f32_e32 v98, v98
	ds_read_b64_tr_b16 v[220:221], v206 offset:0x600
	ds_read_b64_tr_b16 v[222:223], v206 offset:0xe00
	s_waitcnt lgkmcnt(12)
	v_mfma_f32_32x32x16_bf16 v[32:47], v[112:115], v[224:227], v[32:47]
	v_exp_f32_e32 v99, v99
	v_exp_f32_e32 v100, v100
	v_exp_f32_e32 v101, v101
	ds_read_b64_tr_b16 v[224:225], v206 offset:0x1600
	ds_read_b64_tr_b16 v[226:227], v206 offset:0x1e00
	s_waitcnt lgkmcnt(12)
	v_mfma_f32_32x32x16_bf16 v[32:47], v[116:119], v[198:201], v[32:47]
	v_exp_f32_e32 v102, v102
	v_exp_f32_e32 v103, v103
	v_exp_f32_e32 v104, v104
	ds_read_b64_tr_b16 v[198:199], v206 offset:0x2600
	ds_read_b64_tr_b16 v[200:201], v206 offset:0x2e00
	s_waitcnt lgkmcnt(12)
	v_mfma_f32_32x32x16_bf16 v[16:31], v[128:131], v[190:193], v[16:31]
	v_exp_f32_e32 v105, v105
	v_exp_f32_e32 v106, v106
	v_exp_f32_e32 v107, v107
	ds_read_b64_tr_b16 v[190:191], v206 offset:0x3600
	ds_read_b64_tr_b16 v[192:193], v206 offset:0x3e00
	s_waitcnt lgkmcnt(12)
	v_mfma_f32_32x32x16_bf16 v[16:31], v[132:135], v[212:215], v[16:31]
	v_exp_f32_e32 v108, v108
	v_exp_f32_e32 v109, v109
	v_exp_f32_e32 v110, v110
	s_waitcnt lgkmcnt(10)
	v_mfma_f32_32x32x16_bf16 v[16:31], v[112:115], v[202:205], v[16:31]
	v_exp_f32_e32 v111, v111
	v_exp_f32_e32 v80, v80
	v_exp_f32_e32 v81, v81
	s_waitcnt lgkmcnt(8)
	v_mfma_f32_32x32x16_bf16 v[16:31], v[116:119], v[216:219], v[16:31]
	v_exp_f32_e32 v82, v82
	v_exp_f32_e32 v83, v83
	v_exp_f32_e32 v84, v84
	s_waitcnt lgkmcnt(6)
	v_mfma_f32_32x32x16_bf16 v[0:15], v[128:131], v[220:223], v[0:15]
	v_exp_f32_e32 v85, v85
	v_exp_f32_e32 v86, v86
	v_exp_f32_e32 v87, v87
	v_lshl_add_u32 v236, s38, 13, v184
	ds_read_b128 v[228:231], v236 offset:49152
	ds_read_b128 v[232:235], v236 offset:49664
	s_waitcnt lgkmcnt(6)
	v_mfma_f32_32x32x16_bf16 v[0:15], v[132:135], v[224:227], v[0:15]
	v_exp_f32_e32 v88, v88
	v_exp_f32_e32 v89, v89
	v_exp_f32_e32 v90, v90
	s_waitcnt lgkmcnt(4)
	v_mfma_f32_32x32x16_bf16 v[0:15], v[112:115], v[198:201], v[0:15]
	v_exp_f32_e32 v91, v91
	v_exp_f32_e32 v92, v92
	v_exp_f32_e32 v93, v93
	s_waitcnt lgkmcnt(2)
	v_mfma_f32_32x32x16_bf16 v[0:15], v[116:119], v[190:193], v[0:15]
	v_exp_f32_e32 v94, v94
	v_exp_f32_e32 v95, v95
	v_cmp_gt_f32_e32 vcc, 1.0, v185
	s_cbranch_vccz .LBB0_705
	s_and_saveexec_b64 s[70:71], s[0:1]
	ds_write_b32 v177, v185 offset:128
	s_or_b64 exec, exec, s[70:71]
	s_waitcnt lgkmcnt(0)
	v_add_u32_e32 v126, s19, v168
	ds_read_b128 v[112:115], v126 offset:224
	ds_read_b128 v[116:119], v126 offset:192
	ds_read_b128 v[122:125], v126 offset:160
	ds_read_b128 v[126:129], v126 offset:128
	s_waitcnt lgkmcnt(3)
	v_pk_mul_f32 v[60:61], v[60:61], v[112:113]
	s_waitcnt lgkmcnt(2)
	v_pk_mul_f32 v[56:57], v[56:57], v[116:117]
	s_waitcnt lgkmcnt(1)
	v_pk_mul_f32 v[52:53], v[52:53], v[122:123]
	v_pk_mul_f32 v[62:63], v[62:63], v[114:115]
	v_pk_mul_f32 v[58:59], v[58:59], v[118:119]
	v_pk_mul_f32 v[54:55], v[54:55], v[124:125]
	s_waitcnt lgkmcnt(0)
	v_pk_mul_f32 v[50:51], v[50:51], v[128:129]
	v_pk_mul_f32 v[48:49], v[48:49], v[126:127]
	v_pk_mul_f32 v[44:45], v[44:45], v[112:113]
	v_pk_mul_f32 v[40:41], v[40:41], v[116:117]
	v_pk_mul_f32 v[36:37], v[36:37], v[122:123]
	v_pk_mul_f32 v[46:47], v[46:47], v[114:115]
	v_pk_mul_f32 v[42:43], v[42:43], v[118:119]
	v_pk_mul_f32 v[38:39], v[38:39], v[124:125]
	v_pk_mul_f32 v[34:35], v[34:35], v[128:129]
	v_pk_mul_f32 v[32:33], v[32:33], v[126:127]
	v_pk_mul_f32 v[28:29], v[28:29], v[112:113]
	v_pk_mul_f32 v[24:25], v[24:25], v[116:117]
	v_pk_mul_f32 v[20:21], v[20:21], v[122:123]
	v_pk_mul_f32 v[30:31], v[30:31], v[114:115]
	v_pk_mul_f32 v[26:27], v[26:27], v[118:119]
	v_pk_mul_f32 v[22:23], v[22:23], v[124:125]
	v_pk_mul_f32 v[18:19], v[18:19], v[128:129]
	v_pk_mul_f32 v[16:17], v[16:17], v[126:127]
	v_pk_mul_f32 v[12:13], v[12:13], v[112:113]
	v_pk_mul_f32 v[8:9], v[8:9], v[116:117]
	v_pk_mul_f32 v[4:5], v[4:5], v[122:123]
	v_pk_mul_f32 v[14:15], v[14:15], v[114:115]
	v_pk_mul_f32 v[10:11], v[10:11], v[118:119]
	v_pk_mul_f32 v[6:7], v[6:7], v[124:125]
	v_pk_mul_f32 v[2:3], v[2:3], v[128:129]
	v_pk_mul_f32 v[0:1], v[0:1], v[126:127]
.LBB0_705:
	v_add_f32_e32 v112, v186, v187
	s_waitcnt vmcnt(0)
	s_barrier
	s_add_u32 s68, s68, 0x40000
	v_fmac_f32_e32 v112, v178, v182
	v_add_f32_e32 v178, v120, v121
	s_addc_u32 s69, s69, 0
	s_add_i32 s35, s35, 2
	v_fmac_f32_e32 v178, v112, v188
	s_cmpk_gt_u32 s35, 0x80
	v_lshl_add_u64 v[172:173], v[172:173], 0, s[10:11]
	s_cbranch_scc1 .LBB0_709
	s_mov_b32 s44, s34
	s_mov_b32 s34, s42
	v_mov_b32_e32 v182, v185
	s_branch .LBB0_695

; #define WAIT_BAR() asm volatile("s_waitcnt vmcnt(0) lgkmcnt(0)\n\ts_barrier" ::: "memory")
;     ...
;     if (wid >= 4) __builtin_amdgcn_s_setprio(1);
;     DMA(0, 0); DMA(1, 1); WAIT_BAR();
;     { qkt(pA0, pA1, K_lds, qr, r32, hi); rowdecide(rowmax16(pA0), pA0, pA1, negm, alA);
; #pragma unroll
;       for (int r = 0; r < 16; ++r) { pA0[r] = __builtin_amdgcn_exp2f(pA0[r]); pA1[r] = __builtin_amdgcn_exp2f(pA1[r]); } }
;     for (int j = 1; j + 1 < NT; j += 2) {
;       STEP(pB0, pB1, pA0, pA1, alA, alB, DMA(j + 1, sn));
.LBB0_719:
	s_and_b32 s0, s0, 0x3fffffc0
	s_lshl_b32 s0, s0, 2
	s_add_i32 s19, s0, 0
	s_add_i32 s19, s19, 0x12000
	v_lshlrev_b32_e32 v35, 4, v169
	v_lshlrev_b32_e32 v34, 3, v169
	v_and_b32_e32 v35, 0xc0, v35
	v_lshlrev_b32_e32 v36, 1, v169
	s_cmp_lg_u32 0, -1
	v_exp_f32_e32 v96, v16
	v_exp_f32_e32 v80, v0
	v_exp_f32_e32 v97, v17
	v_exp_f32_e32 v81, v1
	v_exp_f32_e32 v98, v18
	v_exp_f32_e32 v82, v2
	v_exp_f32_e32 v99, v19
	v_exp_f32_e32 v83, v3
	v_exp_f32_e32 v100, v20
	v_exp_f32_e32 v84, v4
	v_exp_f32_e32 v101, v21
	v_exp_f32_e32 v85, v5
	v_exp_f32_e32 v102, v22
	v_exp_f32_e32 v86, v6
	v_exp_f32_e32 v103, v23
	v_exp_f32_e32 v87, v7
	v_exp_f32_e32 v104, v24
	v_exp_f32_e32 v88, v8
	v_exp_f32_e32 v105, v25
	v_exp_f32_e32 v89, v9
	v_exp_f32_e32 v106, v26
	v_exp_f32_e32 v90, v10
	v_exp_f32_e32 v107, v27
	v_exp_f32_e32 v91, v11
	v_exp_f32_e32 v108, v28
	v_exp_f32_e32 v92, v12
	v_exp_f32_e32 v109, v29
	v_exp_f32_e32 v93, v13
	v_exp_f32_e32 v110, v30
	v_exp_f32_e32 v94, v14
	v_exp_f32_e32 v111, v31
	v_exp_f32_e32 v95, v15
	v_and_or_b32 v35, v34, 24, v35
	v_and_b32_e32 v36, 32, v36
	v_and_b32_e32 v34, 0x100, v34
	s_cselect_b32 s0, 0, 0
	v_mov_b32_e32 v48, v167
	v_mov_b32_e32 v49, v167
	v_or3_b32 v182, v35, v36, v34
	s_add_i32 s39, s0, s24
	v_lshl_add_u64 v[172:173], v[32:33], 0, s[10:11]
	v_mov_b32_e32 v50, v167
	v_mov_b32_e32 v51, v167
	v_mov_b32_e32 v52, v167
	v_mov_b32_e32 v53, v167
	v_mov_b32_e32 v54, v167
	v_mov_b32_e32 v55, v167
	v_mov_b32_e32 v56, v167
	v_mov_b32_e32 v57, v167
	v_mov_b32_e32 v58, v167
	v_mov_b32_e32 v59, v167
	v_mov_b32_e32 v60, v167
	v_mov_b32_e32 v61, v167
	v_mov_b32_e32 v62, v167
	v_mov_b32_e32 v63, v167
	v_mov_b64_e32 v[32:33], v[48:49]
	v_mov_b64_e32 v[16:17], v[48:49]
	v_mov_b64_e32 v[0:1], v[48:49]
	s_mov_b32 s34, 2
	s_mov_b32 s38, 1
	s_mov_b32 s35, -1
	s_mov_b32 s44, 0
	v_add_u32_e32 v185, s0, v182
	s_add_i32 s39, s39, 0xc000
	v_cmp_gt_u32_e64 s[0:1], 32, v169
	v_lshl_add_u32 v180, v178, 2, s19
	v_add3_u32 v186, 0, v183, v179
	v_mov_b32_e32 v181, 0
	v_mov_b64_e32 v[34:35], v[50:51]
	v_mov_b64_e32 v[36:37], v[52:53]
	v_mov_b64_e32 v[38:39], v[54:55]
	v_mov_b64_e32 v[40:41], v[56:57]
	v_mov_b64_e32 v[42:43], v[58:59]
	v_mov_b64_e32 v[44:45], v[60:61]
	v_mov_b64_e32 v[46:47], v[62:63]
	v_mov_b64_e32 v[18:19], v[50:51]
	v_mov_b64_e32 v[20:21], v[52:53]
	v_mov_b64_e32 v[22:23], v[54:55]
	v_mov_b64_e32 v[24:25], v[56:57]
	v_mov_b64_e32 v[26:27], v[58:59]
	v_mov_b64_e32 v[28:29], v[60:61]
	v_mov_b64_e32 v[30:31], v[62:63]
	v_mov_b64_e32 v[2:3], v[50:51]
	v_mov_b64_e32 v[4:5], v[52:53]
	v_mov_b64_e32 v[6:7], v[54:55]
	v_mov_b64_e32 v[8:9], v[56:57]
	v_mov_b64_e32 v[10:11], v[58:59]
	v_mov_b64_e32 v[12:13], v[60:61]
	v_mov_b64_e32 v[14:15], v[62:63]
	s_lshl_b32 s48, s34, 13
	s_add_i32 s48, s48, s39
	s_mov_b32 m0, s48
	s_nop 0
	global_load_lds_dwordx4 v[172:173], off
	v_lshl_add_u64 v[172:173], v[172:173], 0, s[8:9]
	s_waitcnt vmcnt(0)
	s_barrier
	v_lshl_add_u32 v236, s38, 13, v186
	ds_read_b128 v[228:231], v236 offset:49152
	ds_read_b128 v[232:235], v236 offset:49664
.LBB0_720:
	s_lshl_b32 s43, s34, 13
	s_mov_b32 s42, s38
	v_lshl_add_u32 v187, s42, 13, v186
	s_mov_b32 s38, s44
	s_cmp_lt_i32 s18, 4
	s_cbranch_scc1 .Lattn_nodma_Lattn_m1_res1
	s_lshl_b32 s98, s38, 13
	s_add_i32 s98, s98, s39
	s_mov_b32 m0, s98
	s_mov_b32 s100, 0xffffffc0
	s_mov_b32 s101, -1
	global_load_lds_dwordx4 v[172:173], off
	s_addk_i32 s98, 0xf000
	s_mov_b32 m0, s98
	v_lshl_add_u64 v[212:213], v[172:173], 0, s[100:101]
	global_load_lds_dwordx4 v[212:213], off
	s_lshl_b32 s98, s34, 14
	s_add_i32 s99, s98, s24
	s_mov_b32 m0, s99
	v_lshl_add_u64 v[212:213], s[4:5], 0, v[166:167]
	global_load_lds_dwordx4 v[212:213], off
	s_add_u32 s100, s4, 0xffff8000
	s_addc_u32 s101, s5, -1
	s_addk_i32 s99, 0xf000
	s_mov_b32 m0, s99
	v_lshl_add_u64 v[214:215], s[100:101], 0, v[166:167]
	global_load_lds_dwordx4 v[214:215], off
	s_add_i32 s98, s98, s25
	s_mov_b32 m0, s98
	v_lshl_add_u64 v[212:213], s[4:5], 0, v[170:171]
	global_load_lds_dwordx4 v[212:213], off
	s_addk_i32 s98, 0xf000
	s_mov_b32 m0, s98
	v_lshl_add_u64 v[214:215], s[100:101], 0, v[170:171]
	global_load_lds_dwordx4 v[214:215], off
.Lattn_nodma_Lattn_m1_res1:
	s_waitcnt lgkmcnt(1)
	v_mfma_f32_32x32x16_bf16 v[128:143], v[228:231], v[156:159], v[64:79]
	ds_read_b128 v[192:195], v187 offset:51200
	ds_read_b128 v[196:199], v187 offset:51712
	v_add_f32_e32 v116, v98, v96
	v_add_f32_e32 v117, v99, v97
	v_cvt_pk_bf16_f32 v96, v96, v97
	v_cvt_pk_bf16_f32 v97, v98, v99
	v_cvt_pk_bf16_f32 v98, v100, v101
	v_cvt_pk_bf16_f32 v99, v102, v103
	v_add_f32_e32 v100, v100, v116
	v_add_f32_e32 v101, v101, v117
	s_waitcnt lgkmcnt(2)
	v_mfma_f32_32x32x16_bf16 v[112:127], v[232:235], v[156:159], v[64:79]
	v_add_f32_e32 v100, v102, v100
	v_add_f32_e32 v101, v103, v101
	s_waitcnt lgkmcnt(1)
	v_mfma_f32_32x32x16_bf16 v[128:143], v[192:195], v[152:155], v[128:143]
	ds_read_b128 v[188:191], v187 offset:53248
	ds_read_b128 v[200:203], v187 offset:53760
	v_add_f32_e32 v100, v104, v100
	v_add_f32_e32 v101, v105, v101
	v_add_f32_e32 v204, v106, v100
	v_add_f32_e32 v205, v107, v101
	v_cvt_pk_bf16_f32 v100, v104, v105
	v_cvt_pk_bf16_f32 v101, v106, v107
	v_cvt_pk_bf16_f32 v102, v108, v109
	v_cvt_pk_bf16_f32 v103, v110, v111
	s_waitcnt lgkmcnt(2)
	v_mfma_f32_32x32x16_bf16 v[112:127], v[196:199], v[152:155], v[112:127]
	v_add_f32_e32 v104, v108, v204
	v_add_f32_e32 v105, v109, v205
	v_add_f32_e32 v192, v110, v104
	v_add_f32_e32 v193, v111, v105
	s_waitcnt lgkmcnt(1)
	v_mfma_f32_32x32x16_bf16 v[128:143], v[188:191], v[148:151], v[128:143]
	ds_read_b128 v[104:107], v187 offset:55296
	ds_read_b128 v[108:111], v187 offset:55808
	v_add_f32_e32 v187, v80, v192
	v_add_f32_e32 v192, v81, v193
	v_add_f32_e32 v187, v82, v187
	v_add_f32_e32 v192, v83, v192
	v_cvt_pk_bf16_f32 v80, v80, v81
	v_cvt_pk_bf16_f32 v81, v82, v83
	v_cvt_pk_bf16_f32 v82, v84, v85
	v_cvt_pk_bf16_f32 v83, v86, v87
	s_waitcnt lgkmcnt(2)
	v_mfma_f32_32x32x16_bf16 v[112:127], v[200:203], v[148:151], v[112:127]
	s_lshl_b32 s44, s38, 14
	v_add_u32_e32 v191, s44, v185
	ds_read_b64_tr_b16 v[196:197], v191 offset:0
	ds_read_b64_tr_b16 v[198:199], v191 offset:0x800
	ds_read_b64_tr_b16 v[212:213], v191 offset:0x1000
	ds_read_b64_tr_b16 v[214:215], v191 offset:0x1800
	ds_read_b64_tr_b16 v[216:217], v191 offset:0x2000
	ds_read_b64_tr_b16 v[218:219], v191 offset:0x2800
	v_add_f32_e32 v84, v84, v187
	v_add_f32_e32 v85, v85, v192
	v_add_f32_e32 v84, v86, v84
	v_add_f32_e32 v85, v87, v85
	s_waitcnt lgkmcnt(7)
	v_mfma_f32_32x32x16_bf16 v[128:143], v[104:107], v[144:147], v[128:143]
	ds_read_b64_tr_b16 v[200:201], v191 offset:0x3000
	ds_read_b64_tr_b16 v[202:203], v191 offset:0x3800
	ds_read_b64_tr_b16 v[192:193], v191 offset:0x200
	ds_read_b64_tr_b16 v[194:195], v191 offset:0xa00
	v_add_f32_e32 v84, v88, v84
	v_add_f32_e32 v85, v89, v85
	v_add_f32_e32 v187, v90, v84
	v_add_f32_e32 v188, v91, v85
	v_cvt_pk_bf16_f32 v84, v88, v89
	v_cvt_pk_bf16_f32 v85, v90, v91
	v_cvt_pk_bf16_f32 v86, v92, v93
	v_cvt_pk_bf16_f32 v87, v94, v95
	s_waitcnt lgkmcnt(10)
	v_mfma_f32_32x32x16_bf16 v[112:127], v[108:111], v[144:147], v[112:127]
	v_add_f32_e32 v88, v92, v187
	v_add_f32_e32 v89, v93, v188
	v_add_f32_e32 v88, v94, v88
	v_add_f32_e32 v89, v95, v89
	ds_read_b64_tr_b16 v[220:221], v191 offset:0x1200
	ds_read_b64_tr_b16 v[222:223], v191 offset:0x1a00
	ds_read_b64_tr_b16 v[224:225], v191 offset:0x2200
	ds_read_b64_tr_b16 v[226:227], v191 offset:0x2a00
	s_waitcnt lgkmcnt(12)
	v_mfma_f32_32x32x16_bf16 v[48:63], v[96:99], v[196:199], v[48:63]
	v_max_f32_e32 v90, v128, v129
	v_max3_f32 v91, v131, v132, v133
	v_max3_f32 v90, v90, v130, v134
	v_max3_f32 v91, v91, v136, v137
	ds_read_b64_tr_b16 v[196:197], v191 offset:0x3200
	ds_read_b64_tr_b16 v[198:199], v191 offset:0x3a00
	s_waitcnt lgkmcnt(12)
	v_mfma_f32_32x32x16_bf16 v[48:63], v[100:103], v[212:215], v[48:63]
	v_max3_f32 v90, v90, v135, v138
	v_max3_f32 v91, v91, v140, v141
	v_max3_f32 v90, v90, v139, v142
	v_max3_f32 v90, v90, v143, v91
	v_add_f32_e32 v188, v88, v89
	v_mov_b32_e32 v189, v188
	ds_read_b64_tr_b16 v[212:213], v191 offset:0x400
	ds_read_b64_tr_b16 v[214:215], v191 offset:0xc00
	s_waitcnt lgkmcnt(12)
	v_mfma_f32_32x32x16_bf16 v[48:63], v[80:83], v[216:219], v[48:63]
	v_max3_f32 v88, v112, v113, v114
	v_max3_f32 v89, v115, v116, v117
	v_max3_f32 v88, v88, v118, v119
	v_max3_f32 v89, v89, v120, v121
	v_permlane32_swap_b32_e32 v188, v189
	v_max3_f32 v88, v88, v122, v123
	ds_read_b64_tr_b16 v[216:217], v191 offset:0x1400
	ds_read_b64_tr_b16 v[218:219], v191 offset:0x1c00
	s_waitcnt lgkmcnt(12)
	v_mfma_f32_32x32x16_bf16 v[48:63], v[84:87], v[200:203], v[48:63]
	v_max3_f32 v89, v89, v124, v125
	v_max3_f32 v88, v88, v126, v127
	v_max3_f32 v88, v90, v88, v89
	v_mov_b32_e32 v89, v88
	ds_read_b64_tr_b16 v[200:201], v191 offset:0x2400
	ds_read_b64_tr_b16 v[202:203], v191 offset:0x2c00
	s_waitcnt lgkmcnt(12)
	v_mfma_f32_32x32x16_bf16 v[32:47], v[96:99], v[192:195], v[32:47]
	v_permlane32_swap_b32_e32 v88, v89
	v_max_f32_e32 v88, v88, v89
	v_cmp_lt_f32_e32 vcc, s47, v88
	v_mov_b32_e32 v190, 1.0
	s_cbranch_vccnz .LBB0_732
; #define WAIT_BAR() asm volatile("s_waitcnt vmcnt(0) lgkmcnt(0)\n\ts_barrier" ::: "memory")
; #define RESC(a) do { if (__any((a) < 1.f)) { if (hi == 0) al_l[r32] = (a); asm volatile("s_waitcnt lgkmcnt(0)" ::: "memory"); \
;     _Pragma("unroll") for (int d = 0; d < 4; ++d) _Pragma("unroll") for (int r = 0; r < 16; ++r) o[d][r] *= al_l[crow(r, hi)]; } } while (0)
; #define ROT() do { const int t_ = sp; sp = sc_; sc_ = sn; sn = t_; } while (0)
;     ...
;     if (wid >= 4) __builtin_amdgcn_s_setprio(1);
;     DMA(0, 0); DMA(1, 1); WAIT_BAR();
;     { qkt(pA0, pA1, K_lds, qr, r32, hi); rowdecide(rowmax16(pA0), pA0, pA1, negm, alA);
; #pragma unroll
;       for (int r = 0; r < 16; ++r) { pA0[r] = __builtin_amdgcn_exp2f(pA0[r]); pA1[r] = __builtin_amdgcn_exp2f(pA1[r]); } }
;     for (int j = 1; j + 1 < NT; j += 2) {
;       STEP(pB0, pB1, pA0, pA1, alA, alB, DMA(j + 1, sn));
;       RESC(alB); WAIT_BAR(); ROT();
;       STEP(pA0, pA1, pB0, pB1, alB, alA, DMA(j + 2, sn));
.Lattn_m1_res1:
	ds_read_b64_tr_b16 v[192:193], v191 offset:0x3400
	ds_read_b64_tr_b16 v[194:195], v191 offset:0x3c00
	s_waitcnt lgkmcnt(12)
	v_mfma_f32_32x32x16_bf16 v[32:47], v[100:103], v[220:223], v[32:47]
	v_exp_f32_e32 v128, v128
	v_exp_f32_e32 v129, v129
	v_exp_f32_e32 v130, v130
	ds_read_b64_tr_b16 v[220:221], v191 offset:0x600
	ds_read_b64_tr_b16 v[222:223], v191 offset:0xe00
	s_waitcnt lgkmcnt(12)
	v_mfma_f32_32x32x16_bf16 v[32:47], v[80:83], v[224:227], v[32:47]
	v_exp_f32_e32 v131, v131
	v_exp_f32_e32 v132, v132
	v_exp_f32_e32 v133, v133
	ds_read_b64_tr_b16 v[224:225], v191 offset:0x1600
	ds_read_b64_tr_b16 v[226:227], v191 offset:0x1e00
	s_waitcnt lgkmcnt(12)
	v_mfma_f32_32x32x16_bf16 v[32:47], v[84:87], v[196:199], v[32:47]
	v_exp_f32_e32 v134, v134
	v_exp_f32_e32 v135, v135
	v_exp_f32_e32 v136, v136
	ds_read_b64_tr_b16 v[196:197], v191 offset:0x2600
	ds_read_b64_tr_b16 v[198:199], v191 offset:0x2e00
	s_waitcnt lgkmcnt(12)
	v_mfma_f32_32x32x16_bf16 v[16:31], v[96:99], v[212:215], v[16:31]
	v_exp_f32_e32 v137, v137
	v_exp_f32_e32 v138, v138
	v_exp_f32_e32 v139, v139
	ds_read_b64_tr_b16 v[212:213], v191 offset:0x3600
	ds_read_b64_tr_b16 v[214:215], v191 offset:0x3e00
	s_waitcnt lgkmcnt(12)
	v_mfma_f32_32x32x16_bf16 v[16:31], v[100:103], v[216:219], v[16:31]
	v_exp_f32_e32 v140, v140
	v_exp_f32_e32 v141, v141
	v_exp_f32_e32 v142, v142
	s_waitcnt lgkmcnt(10)
	v_mfma_f32_32x32x16_bf16 v[16:31], v[80:83], v[200:203], v[16:31]
	v_exp_f32_e32 v143, v143
	v_exp_f32_e32 v112, v112
	v_exp_f32_e32 v113, v113
	s_waitcnt lgkmcnt(8)
	v_mfma_f32_32x32x16_bf16 v[16:31], v[84:87], v[192:195], v[16:31]
	v_exp_f32_e32 v114, v114
	v_exp_f32_e32 v115, v115
	v_exp_f32_e32 v116, v116
	s_waitcnt lgkmcnt(6)
	v_mfma_f32_32x32x16_bf16 v[0:15], v[96:99], v[220:223], v[0:15]
	v_exp_f32_e32 v117, v117
	v_exp_f32_e32 v118, v118
	v_exp_f32_e32 v119, v119
	v_lshl_add_u32 v236, s34, 13, v186
	ds_read_b128 v[228:231], v236 offset:49152
	ds_read_b128 v[232:235], v236 offset:49664
	s_waitcnt lgkmcnt(6)
	v_mfma_f32_32x32x16_bf16 v[0:15], v[100:103], v[224:227], v[0:15]
	v_exp_f32_e32 v120, v120
	v_exp_f32_e32 v121, v121
	v_exp_f32_e32 v122, v122
	s_waitcnt lgkmcnt(4)
	v_mfma_f32_32x32x16_bf16 v[0:15], v[80:83], v[196:199], v[0:15]
	v_exp_f32_e32 v123, v123
	v_exp_f32_e32 v124, v124
	v_exp_f32_e32 v125, v125
	s_waitcnt lgkmcnt(2)
	v_mfma_f32_32x32x16_bf16 v[0:15], v[84:87], v[212:215], v[0:15]
	v_exp_f32_e32 v126, v126
	v_exp_f32_e32 v127, v127
	v_cmp_gt_f32_e32 vcc, 1.0, v190
	s_cbranch_vccz .LBB0_725
	s_and_saveexec_b64 s[52:53], s[0:1]
	ds_write_b32 v180, v190 offset:128
	s_or_b64 exec, exec, s[52:53]
	s_waitcnt lgkmcnt(0)
	v_add_u32_e32 v92, s19, v168
	ds_read_b128 v[80:83], v92 offset:224
	ds_read_b128 v[84:87], v92 offset:192
	ds_read_b128 v[88:91], v92 offset:160
	ds_read_b128 v[92:95], v92 offset:128
	s_waitcnt lgkmcnt(3)
	v_pk_mul_f32 v[60:61], v[60:61], v[80:81]
	s_waitcnt lgkmcnt(2)
	v_pk_mul_f32 v[56:57], v[56:57], v[84:85]
	s_waitcnt lgkmcnt(1)
	v_pk_mul_f32 v[52:53], v[52:53], v[88:89]
	v_pk_mul_f32 v[62:63], v[62:63], v[82:83]
	v_pk_mul_f32 v[58:59], v[58:59], v[86:87]
	v_pk_mul_f32 v[54:55], v[54:55], v[90:91]
	s_waitcnt lgkmcnt(0)
	v_pk_mul_f32 v[50:51], v[50:51], v[94:95]
	v_pk_mul_f32 v[48:49], v[48:49], v[92:93]
	v_pk_mul_f32 v[44:45], v[44:45], v[80:81]
	v_pk_mul_f32 v[40:41], v[40:41], v[84:85]
	v_pk_mul_f32 v[36:37], v[36:37], v[88:89]
	v_pk_mul_f32 v[46:47], v[46:47], v[82:83]
	v_pk_mul_f32 v[42:43], v[42:43], v[86:87]
	v_pk_mul_f32 v[38:39], v[38:39], v[90:91]
	v_pk_mul_f32 v[34:35], v[34:35], v[94:95]
	v_pk_mul_f32 v[32:33], v[32:33], v[92:93]
	v_pk_mul_f32 v[28:29], v[28:29], v[80:81]
	v_pk_mul_f32 v[24:25], v[24:25], v[84:85]
	v_pk_mul_f32 v[20:21], v[20:21], v[88:89]
	v_pk_mul_f32 v[30:31], v[30:31], v[82:83]
	v_pk_mul_f32 v[26:27], v[26:27], v[86:87]
	v_pk_mul_f32 v[22:23], v[22:23], v[90:91]
	v_pk_mul_f32 v[18:19], v[18:19], v[94:95]
	v_pk_mul_f32 v[16:17], v[16:17], v[92:93]
	v_pk_mul_f32 v[12:13], v[12:13], v[80:81]
	v_pk_mul_f32 v[8:9], v[8:9], v[84:85]
	v_pk_mul_f32 v[4:5], v[4:5], v[88:89]
	v_pk_mul_f32 v[14:15], v[14:15], v[82:83]
	v_pk_mul_f32 v[10:11], v[10:11], v[86:87]
	v_pk_mul_f32 v[6:7], v[6:7], v[90:91]
	v_pk_mul_f32 v[2:3], v[2:3], v[94:95]
	v_pk_mul_f32 v[0:1], v[0:1], v[92:93]
.LBB0_725:
	s_add_u32 s48, s4, 0x20000
	s_addc_u32 s49, s5, 0
	s_lshl_b32 s45, s42, 13
	s_add_i32 s45, s45, s39
	s_waitcnt vmcnt(0)
	s_barrier
	v_add_u32_e32 v187, s43, v186
	s_cmp_lt_i32 s18, 4
	s_cbranch_scc1 .Lattn_nodma_Lattn_m1_res2
	s_cmp_eq_u32 s35, 0x7f
	s_cbranch_scc1 .Lattn_skipk_Lattn_m1_res2
	s_mov_b32 m0, s45
	v_lshl_add_u64 v[212:213], v[172:173], 0, s[8:9]
	global_load_lds_dwordx4 v[212:213], off
	s_add_i32 s98, s45, 0xfffff000
	s_mov_b32 m0, s98
	s_mov_b32 s100, 0xffffffc0
	s_mov_b32 s101, -1
	v_lshl_add_u64 v[214:215], v[212:213], 0, s[100:101]
	global_load_lds_dwordx4 v[214:215], off

.Lattn_nodma_Lattn_m1_res2:
	s_add_i32 s44, s44, s25
	s_waitcnt lgkmcnt(1)
	v_mfma_f32_32x32x16_bf16 v[96:111], v[228:231], v[156:159], v[64:79]
	ds_read_b128 v[196:199], v187 offset:51200
	ds_read_b128 v[200:203], v187 offset:51712
	v_add_f32_e32 v84, v130, v128
	v_add_f32_e32 v85, v131, v129
	v_cvt_pk_bf16_f32 v128, v128, v129
	v_cvt_pk_bf16_f32 v129, v130, v131
	v_cvt_pk_bf16_f32 v130, v132, v133
	v_cvt_pk_bf16_f32 v131, v134, v135
	v_add_f32_e32 v80, v132, v84
	v_add_f32_e32 v81, v133, v85
	v_add_f32_e32 v132, v134, v80
	v_add_f32_e32 v133, v135, v81
	s_waitcnt lgkmcnt(2)
	v_mfma_f32_32x32x16_bf16 v[80:95], v[232:235], v[156:159], v[64:79]
	s_waitcnt lgkmcnt(1)
	v_mfma_f32_32x32x16_bf16 v[96:111], v[196:199], v[152:155], v[96:111]
	ds_read_b128 v[192:195], v187 offset:53248
	ds_read_b128 v[204:207], v187 offset:53760
	v_add_f32_e32 v132, v136, v132
	v_add_f32_e32 v133, v137, v133
	v_add_f32_e32 v191, v138, v132
	v_add_f32_e32 v208, v139, v133
	v_cvt_pk_bf16_f32 v132, v136, v137
	v_cvt_pk_bf16_f32 v133, v138, v139
	v_cvt_pk_bf16_f32 v134, v140, v141
	v_cvt_pk_bf16_f32 v135, v142, v143
	s_waitcnt lgkmcnt(2)
	v_mfma_f32_32x32x16_bf16 v[80:95], v[200:203], v[152:155], v[80:95]
	v_add_f32_e32 v136, v140, v191
	v_add_f32_e32 v137, v141, v208
	v_add_f32_e32 v191, v142, v136
	v_add_f32_e32 v196, v143, v137
	s_waitcnt lgkmcnt(1)
	v_mfma_f32_32x32x16_bf16 v[96:111], v[192:195], v[148:151], v[96:111]
	ds_read_b128 v[136:139], v187 offset:55296
	ds_read_b128 v[140:143], v187 offset:55808
	v_add_f32_e32 v187, v112, v191
	v_add_f32_e32 v191, v113, v196
	v_add_f32_e32 v187, v114, v187
	v_add_f32_e32 v191, v115, v191
	v_cvt_pk_bf16_f32 v112, v112, v113
	v_cvt_pk_bf16_f32 v113, v114, v115
	v_cvt_pk_bf16_f32 v114, v116, v117
	v_cvt_pk_bf16_f32 v115, v118, v119
	s_waitcnt lgkmcnt(2)
	v_mfma_f32_32x32x16_bf16 v[80:95], v[204:207], v[148:151], v[80:95]
	v_lshl_add_u32 v208, s42, 14, v185
	ds_read_b64_tr_b16 v[200:201], v208 offset:0
	ds_read_b64_tr_b16 v[202:203], v208 offset:0x800
	ds_read_b64_tr_b16 v[192:193], v208 offset:0x1000
	ds_read_b64_tr_b16 v[194:195], v208 offset:0x1800
	ds_read_b64_tr_b16 v[212:213], v208 offset:0x2000
	ds_read_b64_tr_b16 v[214:215], v208 offset:0x2800
	v_add_f32_e32 v116, v116, v187
	v_add_f32_e32 v117, v117, v191
	v_add_f32_e32 v116, v118, v116
	v_add_f32_e32 v117, v119, v117
	s_waitcnt lgkmcnt(7)
	v_mfma_f32_32x32x16_bf16 v[96:111], v[136:139], v[144:147], v[96:111]
	ds_read_b64_tr_b16 v[204:205], v208 offset:0x3000
	ds_read_b64_tr_b16 v[206:207], v208 offset:0x3800
	ds_read_b64_tr_b16 v[216:217], v208 offset:0x200
	ds_read_b64_tr_b16 v[218:219], v208 offset:0xa00
	v_add_f32_e32 v116, v120, v116
	v_add_f32_e32 v117, v121, v117
	v_add_f32_e32 v187, v122, v116
	v_add_f32_e32 v191, v123, v117
	v_cvt_pk_bf16_f32 v116, v120, v121
	v_cvt_pk_bf16_f32 v117, v122, v123
	v_cvt_pk_bf16_f32 v118, v124, v125
	v_cvt_pk_bf16_f32 v119, v126, v127
	s_waitcnt lgkmcnt(10)
	v_mfma_f32_32x32x16_bf16 v[80:95], v[140:143], v[144:147], v[80:95]
	v_add_f32_e32 v120, v124, v187
	v_add_f32_e32 v121, v125, v191
	v_add_f32_e32 v120, v126, v120
	v_add_f32_e32 v121, v127, v121
	ds_read_b64_tr_b16 v[220:221], v208 offset:0x1200
	ds_read_b64_tr_b16 v[222:223], v208 offset:0x1a00
	ds_read_b64_tr_b16 v[224:225], v208 offset:0x2200
	ds_read_b64_tr_b16 v[226:227], v208 offset:0x2a00
	s_waitcnt lgkmcnt(12)
	v_mfma_f32_32x32x16_bf16 v[48:63], v[128:131], v[200:203], v[48:63]
	v_max_f32_e32 v122, v96, v97
	v_max3_f32 v123, v99, v100, v101
	v_max3_f32 v122, v122, v98, v102
	v_max3_f32 v123, v123, v104, v105
	ds_read_b64_tr_b16 v[200:201], v208 offset:0x3200
	ds_read_b64_tr_b16 v[202:203], v208 offset:0x3a00
	s_waitcnt lgkmcnt(12)
	v_mfma_f32_32x32x16_bf16 v[48:63], v[132:135], v[192:195], v[48:63]
	v_max3_f32 v122, v122, v103, v106
	v_max3_f32 v123, v123, v108, v109
	v_max3_f32 v122, v122, v107, v110
	v_max3_f32 v122, v122, v111, v123
	v_add_f32_e32 v120, v120, v121
	v_mov_b32_e32 v121, v120
	ds_read_b64_tr_b16 v[192:193], v208 offset:0x400
	ds_read_b64_tr_b16 v[194:195], v208 offset:0xc00
	s_waitcnt lgkmcnt(12)
	v_mfma_f32_32x32x16_bf16 v[48:63], v[112:115], v[212:215], v[48:63]
	v_max3_f32 v123, v80, v81, v82
	v_max3_f32 v124, v83, v84, v85
	v_max3_f32 v123, v123, v86, v87
	v_max3_f32 v124, v124, v88, v89
	v_permlane32_swap_b32_e32 v120, v121
	v_max3_f32 v123, v123, v90, v91
	ds_read_b64_tr_b16 v[212:213], v208 offset:0x1400
	ds_read_b64_tr_b16 v[214:215], v208 offset:0x1c00
	s_waitcnt lgkmcnt(12)
	v_mfma_f32_32x32x16_bf16 v[48:63], v[116:119], v[204:207], v[48:63]
	v_max3_f32 v124, v124, v92, v93
	v_max3_f32 v123, v123, v94, v95
	v_max3_f32 v122, v122, v123, v124
	v_mov_b32_e32 v123, v122
	ds_read_b64_tr_b16 v[204:205], v208 offset:0x2400
	ds_read_b64_tr_b16 v[206:207], v208 offset:0x2c00
	s_waitcnt lgkmcnt(12)
	v_mfma_f32_32x32x16_bf16 v[32:47], v[128:131], v[216:219], v[32:47]
	v_permlane32_swap_b32_e32 v122, v123
	v_max_f32_e32 v122, v122, v123
	v_cmp_lt_f32_e32 vcc, s47, v122
	v_mov_b32_e32 v187, 1.0
	s_cbranch_vccnz .LBB0_733
; #define WAIT_BAR() asm volatile("s_waitcnt vmcnt(0) lgkmcnt(0)\n\ts_barrier" ::: "memory")
; #define RESC(a) do { if (__any((a) < 1.f)) { if (hi == 0) al_l[r32] = (a); asm volatile("s_waitcnt lgkmcnt(0)" ::: "memory"); \
;     _Pragma("unroll") for (int d = 0; d < 4; ++d) _Pragma("unroll") for (int r = 0; r < 16; ++r) o[d][r] *= al_l[crow(r, hi)]; } } while (0)
; #define ROT() do { const int t_ = sp; sp = sc_; sc_ = sn; sn = t_; } while (0)
;     ...
;     if (wid >= 4) __builtin_amdgcn_s_setprio(1);
;     DMA(0, 0); DMA(1, 1); WAIT_BAR();
;     { qkt(pA0, pA1, K_lds, qr, r32, hi); rowdecide(rowmax16(pA0), pA0, pA1, negm, alA);
; #pragma unroll
;       for (int r = 0; r < 16; ++r) { pA0[r] = __builtin_amdgcn_exp2f(pA0[r]); pA1[r] = __builtin_amdgcn_exp2f(pA1[r]); } }
;     for (int j = 1; j + 1 < NT; j += 2) {
;       STEP(pB0, pB1, pA0, pA1, alA, alB, DMA(j + 1, sn));
;       RESC(alB); WAIT_BAR(); ROT();
;       STEP(pA0, pA1, pB0, pB1, alB, alA, DMA(j + 2, sn));
;       RESC(alA); WAIT_BAR(); ROT();
.Lattn_m1_res2:
	ds_read_b64_tr_b16 v[216:217], v208 offset:0x3400
	ds_read_b64_tr_b16 v[218:219], v208 offset:0x3c00
	s_waitcnt lgkmcnt(12)
	v_mfma_f32_32x32x16_bf16 v[32:47], v[132:135], v[220:223], v[32:47]
	v_exp_f32_e32 v96, v96
	v_exp_f32_e32 v97, v97
	v_exp_f32_e32 v98, v98
	ds_read_b64_tr_b16 v[220:221], v208 offset:0x600
	ds_read_b64_tr_b16 v[222:223], v208 offset:0xe00
	s_waitcnt lgkmcnt(12)
	v_mfma_f32_32x32x16_bf16 v[32:47], v[112:115], v[224:227], v[32:47]
	v_exp_f32_e32 v99, v99
	v_exp_f32_e32 v100, v100
	v_exp_f32_e32 v101, v101
	ds_read_b64_tr_b16 v[224:225], v208 offset:0x1600
	ds_read_b64_tr_b16 v[226:227], v208 offset:0x1e00
	s_waitcnt lgkmcnt(12)
	v_mfma_f32_32x32x16_bf16 v[32:47], v[116:119], v[200:203], v[32:47]
	v_exp_f32_e32 v102, v102
	v_exp_f32_e32 v103, v103
	v_exp_f32_e32 v104, v104
	ds_read_b64_tr_b16 v[200:201], v208 offset:0x2600
	ds_read_b64_tr_b16 v[202:203], v208 offset:0x2e00
	s_waitcnt lgkmcnt(12)
	v_mfma_f32_32x32x16_bf16 v[16:31], v[128:131], v[192:195], v[16:31]
	v_exp_f32_e32 v105, v105
	v_exp_f32_e32 v106, v106
	v_exp_f32_e32 v107, v107
	ds_read_b64_tr_b16 v[192:193], v208 offset:0x3600
	ds_read_b64_tr_b16 v[194:195], v208 offset:0x3e00
	s_waitcnt lgkmcnt(12)
	v_mfma_f32_32x32x16_bf16 v[16:31], v[132:135], v[212:215], v[16:31]
	v_exp_f32_e32 v108, v108
	v_exp_f32_e32 v109, v109
	v_exp_f32_e32 v110, v110
	s_waitcnt lgkmcnt(10)
	v_mfma_f32_32x32x16_bf16 v[16:31], v[112:115], v[204:207], v[16:31]
	v_exp_f32_e32 v111, v111
	v_exp_f32_e32 v80, v80
	v_exp_f32_e32 v81, v81
	s_waitcnt lgkmcnt(8)
	v_mfma_f32_32x32x16_bf16 v[16:31], v[116:119], v[216:219], v[16:31]
	v_exp_f32_e32 v82, v82
	v_exp_f32_e32 v83, v83
	v_exp_f32_e32 v84, v84
	s_waitcnt lgkmcnt(6)
	v_mfma_f32_32x32x16_bf16 v[0:15], v[128:131], v[220:223], v[0:15]
	v_exp_f32_e32 v85, v85
	v_exp_f32_e32 v86, v86
	v_exp_f32_e32 v87, v87
	v_lshl_add_u32 v236, s38, 13, v186
	ds_read_b128 v[228:231], v236 offset:49152
	ds_read_b128 v[232:235], v236 offset:49664
	s_waitcnt lgkmcnt(6)
	v_mfma_f32_32x32x16_bf16 v[0:15], v[132:135], v[224:227], v[0:15]
	v_exp_f32_e32 v88, v88
	v_exp_f32_e32 v89, v89
	v_exp_f32_e32 v90, v90
	s_waitcnt lgkmcnt(4)
	v_mfma_f32_32x32x16_bf16 v[0:15], v[112:115], v[200:203], v[0:15]
	v_exp_f32_e32 v91, v91
	v_exp_f32_e32 v92, v92
	v_exp_f32_e32 v93, v93
	s_waitcnt lgkmcnt(2)
	v_mfma_f32_32x32x16_bf16 v[0:15], v[116:119], v[192:195], v[0:15]
	v_exp_f32_e32 v94, v94
	v_exp_f32_e32 v95, v95
	v_cmp_gt_f32_e32 vcc, 1.0, v187
	s_cbranch_vccz .LBB0_730
	s_and_saveexec_b64 s[52:53], s[0:1]
	ds_write_b32 v180, v187 offset:128
	s_or_b64 exec, exec, s[52:53]
	s_waitcnt lgkmcnt(0)
	v_add_u32_e32 v126, s19, v168
	ds_read_b128 v[112:115], v126 offset:224
	ds_read_b128 v[116:119], v126 offset:192
	ds_read_b128 v[122:125], v126 offset:160
	ds_read_b128 v[126:129], v126 offset:128
	s_waitcnt lgkmcnt(3)
	v_pk_mul_f32 v[60:61], v[60:61], v[112:113]
	s_waitcnt lgkmcnt(2)
	v_pk_mul_f32 v[56:57], v[56:57], v[116:117]
	s_waitcnt lgkmcnt(1)
	v_pk_mul_f32 v[52:53], v[52:53], v[122:123]
	v_pk_mul_f32 v[62:63], v[62:63], v[114:115]
	v_pk_mul_f32 v[58:59], v[58:59], v[118:119]
	v_pk_mul_f32 v[54:55], v[54:55], v[124:125]
	s_waitcnt lgkmcnt(0)
	v_pk_mul_f32 v[50:51], v[50:51], v[128:129]
	v_pk_mul_f32 v[48:49], v[48:49], v[126:127]
	v_pk_mul_f32 v[44:45], v[44:45], v[112:113]
	v_pk_mul_f32 v[40:41], v[40:41], v[116:117]
	v_pk_mul_f32 v[36:37], v[36:37], v[122:123]
	v_pk_mul_f32 v[46:47], v[46:47], v[114:115]
	v_pk_mul_f32 v[42:43], v[42:43], v[118:119]
	v_pk_mul_f32 v[38:39], v[38:39], v[124:125]
	v_pk_mul_f32 v[34:35], v[34:35], v[128:129]
	v_pk_mul_f32 v[32:33], v[32:33], v[126:127]
	v_pk_mul_f32 v[28:29], v[28:29], v[112:113]
	v_pk_mul_f32 v[24:25], v[24:25], v[116:117]
	v_pk_mul_f32 v[20:21], v[20:21], v[122:123]
	v_pk_mul_f32 v[30:31], v[30:31], v[114:115]
	v_pk_mul_f32 v[26:27], v[26:27], v[118:119]
	v_pk_mul_f32 v[22:23], v[22:23], v[124:125]
	v_pk_mul_f32 v[18:19], v[18:19], v[128:129]
	v_pk_mul_f32 v[16:17], v[16:17], v[126:127]
	v_pk_mul_f32 v[12:13], v[12:13], v[112:113]
	v_pk_mul_f32 v[8:9], v[8:9], v[116:117]
	v_pk_mul_f32 v[4:5], v[4:5], v[122:123]
	v_pk_mul_f32 v[14:15], v[14:15], v[114:115]
	v_pk_mul_f32 v[10:11], v[10:11], v[118:119]
	v_pk_mul_f32 v[6:7], v[6:7], v[124:125]
	v_pk_mul_f32 v[2:3], v[2:3], v[128:129]
	v_pk_mul_f32 v[0:1], v[0:1], v[126:127]
.LBB0_730:
	v_add_f32_e32 v112, v188, v189
	s_waitcnt vmcnt(0)
	s_barrier
	s_add_u32 s4, s4, 0x40000
	v_fmac_f32_e32 v112, v181, v184
	v_add_f32_e32 v181, v120, v121
	s_addc_u32 s5, s5, 0
	s_add_i32 s35, s35, 2
	v_fmac_f32_e32 v181, v112, v190
	s_cmpk_gt_u32 s35, 0x80
	v_lshl_add_u64 v[172:173], v[172:173], 0, s[10:11]
	s_cbranch_scc1 .LBB0_734
	s_mov_b32 s44, s34
	s_mov_b32 s34, s42
	v_mov_b32_e32 v184, v187
	s_branch .LBB0_720
